# also removed the compiler-inserted vmcnt(0) before the three single-unit GEMM K-loops (down-projection halves, memory K/V projection)
# speedup vs baseline: 1.0027x; 1.0027x over previous
.LBB0_436:
	s_lshl_b32 s3, s3, 5
	v_lshl_or_b32 v131, s8, 6, v156
	s_lshl_b32 s8, s8, 13
	s_and_b32 s23, s3, 0x60
	v_lshlrev_b32_e32 v3, 2, v156
	s_add_u32 s12, s0, 0x8000
	v_lshl_or_b32 v2, v156, 6, v138
	v_and_b32_e32 v3, 32, v3
	s_addc_u32 s13, s1, 0
	v_bitop3_b32 v4, v2, s8, v3 bitop3:0xde
	s_add_i32 m0, s19, 0x18000
	v_lshl_add_u64 v[2:3], s[12:13], 0, v[142:143]
	s_waitcnt vmcnt(2)
	s_barrier
	global_load_lds_dwordx4 v[2:3], off
	s_add_i32 m0, s19, 0x1a000
	v_lshl_add_u64 v[2:3], s[12:13], 0, v[146:147]
	s_add_u32 s12, s6, 0x8000
	s_addc_u32 s13, s7, 0
	s_add_i32 s24, s19, 0x8000
	global_load_lds_dwordx4 v[2:3], off
	v_lshl_add_u64 v[2:3], s[12:13], 0, v[140:141]
	s_mov_b32 m0, s24
	s_add_i32 s25, s19, 0xa000
	global_load_lds_dwordx4 v[2:3], off
	v_lshl_add_u64 v[2:3], s[12:13], 0, v[144:145]
	s_add_u32 s12, s0, 0xc000
	s_mov_b32 m0, s25
	s_addc_u32 s13, s1, 0
	global_load_lds_dwordx4 v[2:3], off
	s_add_i32 m0, s19, 0x1c000
	v_lshl_add_u64 v[2:3], s[12:13], 0, v[142:143]
	global_load_lds_dwordx4 v[2:3], off
	v_lshl_add_u64 v[2:3], s[12:13], 0, v[146:147]
	s_add_i32 m0, s19, 0x1e000
	s_mul_i32 s3, s86, 0x1800000
	global_load_lds_dwordx4 v[2:3], off
	v_and_b32_e32 v2, 0x1800, v150
	v_lshlrev_b32_e32 v6, 7, v154
	s_add_u32 s8, s3, s10
	s_mul_hi_i32 s3, s86, 0x1800000
	v_or3_b32 v2, v152, v2, v6
	s_addc_u32 s9, s3, s9
	v_add_u32_e32 v2, v2, v153
	v_mov_b32_e32 v3, v143
	v_readlane_b32 s10, v252, 9
	v_lshl_add_u64 v[2:3], s[8:9], 0, v[2:3]
	s_mul_hi_i32 s3, s10, 0x160000
	s_mul_i32 s10, s10, 0x160000
	v_mov_b32_e32 v7, s3
	v_subrev_co_u32_e32 v2, vcc, s10, v2
	v_lshl_or_b32 v5, s23, 7, v157
	s_nop 0
	v_subb_co_u32_e32 v3, vcc, v3, v7, vcc
	v_lshl_add_u64 v[148:149], s[78:79], 0, v[2:3]
	v_and_b32_e32 v2, 0x3800, v155
	v_or3_b32 v2, v152, v2, v6
	v_add_u32_e32 v2, v2, v153
	v_mov_b32_e32 v3, v143
	v_lshl_add_u64 v[2:3], s[8:9], 0, v[2:3]
	s_waitcnt vmcnt(6)
	v_mov_b32_e32 v6, s3
	v_subrev_co_u32_e32 v2, vcc, s10, v2
	s_add_i32 s29, 0, 0x10000
	s_add_i32 s31, 0, 0x14000
	s_add_i32 s35, 0, 0x18000
	s_add_i32 s37, 0, 0x1c000
	v_subb_co_u32_e32 v3, vcc, v3, v6, vcc
	v_add_u32_e32 v133, s29, v5
	v_add_u32_e32 v135, s31, v5
	s_add_i32 s29, s29, s2
	s_add_i32 s31, s31, s2
	v_add_u32_e32 v139, s35, v5
	v_add_u32_e32 v159, s37, v5
	s_add_i32 s35, s35, s2
	s_add_i32 s37, s37, s2
	v_lshl_add_u64 v[150:151], s[78:79], 0, v[2:3]
	s_mov_b32 s26, -2
	s_mov_b64 s[8:9], 0x10000
	v_add_u32_e32 v137, 0, v4
	s_mov_b64 s[10:11], 0x87fc000
	s_add_i32 s27, s19, 0xc000
	s_add_i32 s28, s19, 0xe000
	s_add_i32 s30, s29, 0x2000
	s_add_i32 s34, s31, 0x2000
	s_add_i32 s36, s35, 0x2000
	s_add_i32 s38, s37, 0x2000
	v_mov_b32_e32 v2, v143
	v_mov_b32_e32 v3, v143
	v_mov_b32_e32 v4, v143
	v_mov_b32_e32 v5, v143
	v_mov_b32_e32 v6, v143
	v_mov_b32_e32 v7, v143
	v_mov_b32_e32 v8, v143
	v_mov_b32_e32 v9, v143
	v_mov_b32_e32 v14, v143
	v_mov_b32_e32 v15, v143
	v_mov_b32_e32 v16, v143
	v_mov_b32_e32 v17, v143
	v_mov_b32_e32 v22, v143
	v_mov_b32_e32 v23, v143
	v_mov_b32_e32 v24, v143
	v_mov_b32_e32 v25, v143
	v_mov_b32_e32 v30, v143
	v_mov_b32_e32 v31, v143
	v_mov_b32_e32 v32, v143
	v_mov_b32_e32 v33, v143
	v_mov_b32_e32 v38, v143
	v_mov_b32_e32 v39, v143
	v_mov_b32_e32 v40, v143
	v_mov_b32_e32 v41, v143
	v_mov_b32_e32 v46, v143
	v_mov_b32_e32 v47, v143
	v_mov_b32_e32 v48, v143
	v_mov_b32_e32 v49, v143
	v_mov_b32_e32 v54, v143
	v_mov_b32_e32 v55, v143
	v_mov_b32_e32 v56, v143
	v_mov_b32_e32 v57, v143
	v_mov_b32_e32 v10, v143
	v_mov_b32_e32 v11, v143
	v_mov_b32_e32 v12, v143
	v_mov_b32_e32 v13, v143
	v_mov_b32_e32 v18, v143
	v_mov_b32_e32 v19, v143
	v_mov_b32_e32 v20, v143
	v_mov_b32_e32 v21, v143
	v_mov_b32_e32 v26, v143
	v_mov_b32_e32 v27, v143
	v_mov_b32_e32 v28, v143
	v_mov_b32_e32 v29, v143
	v_mov_b32_e32 v34, v143
	v_mov_b32_e32 v35, v143
	v_mov_b32_e32 v36, v143
	v_mov_b32_e32 v37, v143
	v_mov_b32_e32 v42, v143
	v_mov_b32_e32 v43, v143
	v_mov_b32_e32 v44, v143
	v_mov_b32_e32 v45, v143
	v_mov_b32_e32 v50, v143
	v_mov_b32_e32 v51, v143
	v_mov_b32_e32 v52, v143
	v_mov_b32_e32 v53, v143
	v_mov_b32_e32 v58, v143
	v_mov_b32_e32 v59, v143
	v_mov_b32_e32 v60, v143
	v_mov_b32_e32 v61, v143
	v_mov_b32_e32 v62, v143
	v_mov_b32_e32 v63, v143
	v_mov_b32_e32 v64, v143
	v_mov_b32_e32 v65, v143
	v_mov_b32_e32 v66, v143
	v_mov_b32_e32 v67, v143
	v_mov_b32_e32 v68, v143
	v_mov_b32_e32 v69, v143
	v_mov_b32_e32 v70, v143
	v_mov_b32_e32 v71, v143
	v_mov_b32_e32 v72, v143
	v_mov_b32_e32 v73, v143
	v_mov_b32_e32 v78, v143
	v_mov_b32_e32 v79, v143
	v_mov_b32_e32 v80, v143
	v_mov_b32_e32 v81, v143
	v_mov_b32_e32 v86, v143
	v_mov_b32_e32 v87, v143
	v_mov_b32_e32 v88, v143
	v_mov_b32_e32 v89, v143
	v_mov_b32_e32 v94, v143
	v_mov_b32_e32 v95, v143
	v_mov_b32_e32 v96, v143
	v_mov_b32_e32 v97, v143
	v_mov_b32_e32 v102, v143
	v_mov_b32_e32 v103, v143
	v_mov_b32_e32 v104, v143
	v_mov_b32_e32 v105, v143
	v_mov_b32_e32 v110, v143
	v_mov_b32_e32 v111, v143
	v_mov_b32_e32 v112, v143
	v_mov_b32_e32 v113, v143
	v_mov_b32_e32 v118, v143
	v_mov_b32_e32 v119, v143
	v_mov_b32_e32 v120, v143
	v_mov_b32_e32 v121, v143
	v_mov_b32_e32 v74, v143
	v_mov_b32_e32 v75, v143
	v_mov_b32_e32 v76, v143
	v_mov_b32_e32 v77, v143
	v_mov_b32_e32 v82, v143
	v_mov_b32_e32 v83, v143
	v_mov_b32_e32 v84, v143
	v_mov_b32_e32 v85, v143
	v_mov_b32_e32 v90, v143
	v_mov_b32_e32 v91, v143
	v_mov_b32_e32 v92, v143
	v_mov_b32_e32 v93, v143
	v_mov_b32_e32 v98, v143
	v_mov_b32_e32 v99, v143
	v_mov_b32_e32 v100, v143
	v_mov_b32_e32 v101, v143
	v_mov_b32_e32 v106, v143
	v_mov_b32_e32 v107, v143
	v_mov_b32_e32 v108, v143
	v_mov_b32_e32 v109, v143
	v_mov_b32_e32 v114, v143
	v_mov_b32_e32 v115, v143
	v_mov_b32_e32 v116, v143
	v_mov_b32_e32 v117, v143
	v_mov_b32_e32 v122, v143
	v_mov_b32_e32 v123, v143
	v_mov_b32_e32 v124, v143
	v_mov_b32_e32 v125, v143
	v_mov_b32_e32 v126, v143
	v_mov_b32_e32 v127, v143
	v_mov_b32_e32 v128, v143
	v_mov_b32_e32 v129, v143
	s_barrier

.LBB0_645:
	v_and_b32_e32 v14, 15, v0
	v_lshlrev_b32_e32 v15, 1, v144
	v_lshlrev_b32_e32 v16, 2, v0
	v_lshl_or_b32 v145, s9, 6, v14
	v_lshl_or_b32 v14, v14, 6, v15
	s_lshl_b32 s9, s9, 13
	v_and_b32_e32 v16, 32, v16
	s_lshl_b32 s8, s8, 5
	v_bitop3_b32 v14, v14, s9, v16 bitop3:0xde
	s_and_b32 s21, s8, 0x60
	v_lshlrev_b32_e32 v16, 6, v0
	s_movk_i32 s8, 0x3c0
	v_and_or_b32 v15, v16, s8, v15
	s_lshl_b32 s8, s21, 7
	v_and_b32_e32 v16, 32, v73
	v_bitop3_b32 v15, s8, v15, v16 bitop3:0xf6
	s_mov_b64 s[8:9], 0x80
	s_add_i32 m0, s18, 0x18000
	v_lshl_add_u64 v[8:9], v[8:9], 0, s[8:9]
	s_waitcnt vmcnt(2)
	s_barrier
	global_load_lds_dwordx4 v[8:9], off
	v_lshl_add_u64 v[6:7], v[6:7], 0, s[8:9]
	s_add_i32 m0, s18, 0x1a000
	s_add_i32 s22, s18, 0x8000
	s_add_i32 s23, s18, 0xa000
	global_load_lds_dwordx4 v[6:7], off
	v_lshl_add_u64 v[4:5], v[4:5], 0, s[8:9]
	s_mov_b32 m0, s22
	s_add_u32 s10, s4, 0x40080
	global_load_lds_dwordx4 v[4:5], off
	v_lshl_add_u64 v[2:3], v[2:3], 0, s[8:9]
	s_mov_b32 m0, s23
	s_addc_u32 s11, s5, 0
	global_load_lds_dwordx4 v[2:3], off
	s_add_i32 m0, s18, 0x1c000
	v_lshl_add_u64 v[2:3], s[10:11], 0, v[134:135]
	global_load_lds_dwordx4 v[2:3], off
	v_lshl_add_u64 v[2:3], s[10:11], 0, v[130:131]
	s_add_i32 m0, s18, 0x1e000
	v_lshlrev_b32_e32 v4, 11, v13
	global_load_lds_dwordx4 v[2:3], off
	v_lshlrev_b32_e32 v2, 15, v143
	s_add_u32 s10, s78, s2
	v_or3_b32 v2, v11, v2, v4
	s_addc_u32 s11, s79, s3
	v_add_u32_e32 v2, v2, v12
	v_mov_b32_e32 v3, v135
	v_lshl_add_u64 v[2:3], s[10:11], 0, v[2:3]
	s_mov_b64 s[2:3], 0x3440080
	v_lshl_add_u64 v[138:139], v[2:3], 0, s[2:3]
	v_lshlrev_b32_e32 v2, 4, v10
	v_and_b32_e32 v2, 0x38000, v2
	v_or3_b32 v2, v11, v2, v4
	v_add_u32_e32 v2, v2, v12
	v_mov_b32_e32 v3, v135
	v_lshl_add_u64 v[2:3], s[10:11], 0, v[2:3]
	v_lshl_add_u64 v[140:141], v[2:3], 0, s[2:3]
	s_add_u32 s2, s78, s12
	s_addc_u32 s3, s79, 0
	s_add_u32 s24, s2, 0x2e00100
	s_waitcnt vmcnt(6)
	s_addc_u32 s25, s3, 0
	s_add_i32 s29, 0, 0x10000
	s_add_i32 s31, 0, 0x14000
	s_add_i32 s35, 0, 0x18000
	s_add_i32 s37, 0, 0x1c000
	v_add_u32_e32 v146, s29, v15
	v_add_u32_e32 v147, s31, v15
	s_add_i32 s29, s29, s14
	s_add_i32 s31, s31, s14
	v_add_u32_e32 v149, s35, v15
	v_add_u32_e32 v150, s37, v15
	s_add_i32 s35, s35, s14
	s_add_i32 s37, s37, s14
	s_mov_b32 s26, -2
	s_mov_b64 s[12:13], 0
	v_add_u32_e32 v148, 0, v14
	s_add_i32 s27, s18, 0xc000
	s_add_i32 s28, s18, 0xe000
	s_add_i32 s30, s29, 0x2000
	s_add_i32 s34, s31, 0x2000
	s_add_i32 s36, s35, 0x2000
	s_add_i32 s38, s37, 0x2000
	v_mov_b32_e32 v2, v135
	v_mov_b32_e32 v3, v135
	v_mov_b32_e32 v4, v135
	v_mov_b32_e32 v5, v135
	v_mov_b32_e32 v6, v135
	v_mov_b32_e32 v7, v135
	v_mov_b32_e32 v8, v135
	v_mov_b32_e32 v9, v135
	v_mov_b32_e32 v14, v135
	v_mov_b32_e32 v15, v135
	v_mov_b32_e32 v16, v135
	v_mov_b32_e32 v17, v135
	v_mov_b32_e32 v22, v135
	v_mov_b32_e32 v23, v135
	v_mov_b32_e32 v24, v135
	v_mov_b32_e32 v25, v135
	v_mov_b32_e32 v30, v135
	v_mov_b32_e32 v31, v135
	v_mov_b32_e32 v32, v135
	v_mov_b32_e32 v33, v135
	v_mov_b32_e32 v38, v135
	v_mov_b32_e32 v39, v135
	v_mov_b32_e32 v40, v135
	v_mov_b32_e32 v41, v135
	v_mov_b32_e32 v46, v135
	v_mov_b32_e32 v47, v135
	v_mov_b32_e32 v48, v135
	v_mov_b32_e32 v49, v135
	v_mov_b32_e32 v54, v135
	v_mov_b32_e32 v55, v135
	v_mov_b32_e32 v56, v135
	v_mov_b32_e32 v57, v135
	v_mov_b32_e32 v10, v135
	v_mov_b32_e32 v11, v135
	v_mov_b32_e32 v12, v135
	v_mov_b32_e32 v13, v135
	v_mov_b32_e32 v18, v135
	v_mov_b32_e32 v19, v135
	v_mov_b32_e32 v20, v135
	v_mov_b32_e32 v21, v135
	v_mov_b32_e32 v26, v135
	v_mov_b32_e32 v27, v135
	v_mov_b32_e32 v28, v135
	v_mov_b32_e32 v29, v135
	v_mov_b32_e32 v34, v135
	v_mov_b32_e32 v35, v135
	v_mov_b32_e32 v36, v135
	v_mov_b32_e32 v37, v135
	v_mov_b32_e32 v42, v135
	v_mov_b32_e32 v43, v135
	v_mov_b32_e32 v44, v135
	v_mov_b32_e32 v45, v135
	v_mov_b32_e32 v50, v135
	v_mov_b32_e32 v51, v135
	v_mov_b32_e32 v52, v135
	v_mov_b32_e32 v53, v135
	v_mov_b32_e32 v58, v135
	v_mov_b32_e32 v59, v135
	v_mov_b32_e32 v60, v135
	v_mov_b32_e32 v61, v135
	v_mov_b32_e32 v62, v135
	v_mov_b32_e32 v63, v135
	v_mov_b32_e32 v64, v135
	v_mov_b32_e32 v65, v135
	v_mov_b32_e32 v66, v135
	v_mov_b32_e32 v67, v135
	v_mov_b32_e32 v68, v135
	v_mov_b32_e32 v69, v135
	v_mov_b32_e32 v70, v135
	v_mov_b32_e32 v71, v135
	v_mov_b32_e32 v72, v135
	v_mov_b32_e32 v73, v135
	v_mov_b32_e32 v78, v135
	v_mov_b32_e32 v79, v135
	v_mov_b32_e32 v80, v135
	v_mov_b32_e32 v81, v135
	v_mov_b32_e32 v86, v135
	v_mov_b32_e32 v87, v135
	v_mov_b32_e32 v88, v135
	v_mov_b32_e32 v89, v135
	v_mov_b32_e32 v94, v135
	v_mov_b32_e32 v95, v135
	v_mov_b32_e32 v96, v135
	v_mov_b32_e32 v97, v135
	v_mov_b32_e32 v102, v135
	v_mov_b32_e32 v103, v135
	v_mov_b32_e32 v104, v135
	v_mov_b32_e32 v105, v135
	v_mov_b32_e32 v110, v135
	v_mov_b32_e32 v111, v135
	v_mov_b32_e32 v112, v135
	v_mov_b32_e32 v113, v135
	v_mov_b32_e32 v118, v135
	v_mov_b32_e32 v119, v135
	v_mov_b32_e32 v120, v135
	v_mov_b32_e32 v121, v135
	v_mov_b32_e32 v74, v135
	v_mov_b32_e32 v75, v135
	v_mov_b32_e32 v76, v135
	v_mov_b32_e32 v77, v135
	v_mov_b32_e32 v82, v135
	v_mov_b32_e32 v83, v135
	v_mov_b32_e32 v84, v135
	v_mov_b32_e32 v85, v135
	v_mov_b32_e32 v90, v135
	v_mov_b32_e32 v91, v135
	v_mov_b32_e32 v92, v135
	v_mov_b32_e32 v93, v135
	v_mov_b32_e32 v98, v135
	v_mov_b32_e32 v99, v135
	v_mov_b32_e32 v100, v135
	v_mov_b32_e32 v101, v135
	v_mov_b32_e32 v106, v135
	v_mov_b32_e32 v107, v135
	v_mov_b32_e32 v108, v135
	v_mov_b32_e32 v109, v135
	v_mov_b32_e32 v114, v135
	v_mov_b32_e32 v115, v135
	v_mov_b32_e32 v116, v135
	v_mov_b32_e32 v117, v135
	v_mov_b32_e32 v122, v135
	v_mov_b32_e32 v123, v135
	v_mov_b32_e32 v124, v135
	v_mov_b32_e32 v125, v135
	v_mov_b32_e32 v126, v135
	v_mov_b32_e32 v127, v135
	v_mov_b32_e32 v128, v135
	v_mov_b32_e32 v129, v135
	s_barrier

.LBB0_1385:
	s_lshl_b32 s3, s3, 5
	v_lshl_or_b32 v131, s8, 6, v155
	s_lshl_b32 s8, s8, 13
	s_and_b32 s23, s3, 0x60
	v_lshlrev_b32_e32 v3, 2, v155
	s_add_u32 s12, s0, 0x8000
	v_lshl_or_b32 v2, v155, 6, v138
	v_and_b32_e32 v3, 32, v3
	s_addc_u32 s13, s1, 0
	v_bitop3_b32 v4, v2, s8, v3 bitop3:0xde
	s_add_i32 m0, s19, 0x18000
	v_lshl_add_u64 v[2:3], s[12:13], 0, v[142:143]
	s_waitcnt vmcnt(2)
	s_barrier
	global_load_lds_dwordx4 v[2:3], off
	s_add_i32 m0, s19, 0x1a000
	v_lshl_add_u64 v[2:3], s[12:13], 0, v[146:147]
	s_add_u32 s12, s6, 0x8000
	s_addc_u32 s13, s7, 0
	s_add_i32 s24, s19, 0x8000
	global_load_lds_dwordx4 v[2:3], off
	v_lshl_add_u64 v[2:3], s[12:13], 0, v[140:141]
	s_mov_b32 m0, s24
	s_add_i32 s25, s19, 0xa000
	global_load_lds_dwordx4 v[2:3], off
	v_lshl_add_u64 v[2:3], s[12:13], 0, v[144:145]
	s_add_u32 s12, s0, 0xc000
	s_mov_b32 m0, s25
	s_addc_u32 s13, s1, 0
	global_load_lds_dwordx4 v[2:3], off
	s_add_i32 m0, s19, 0x1c000
	v_lshl_add_u64 v[2:3], s[12:13], 0, v[142:143]
	global_load_lds_dwordx4 v[2:3], off
	v_lshl_add_u64 v[2:3], s[12:13], 0, v[146:147]
	s_add_i32 m0, s19, 0x1e000
	v_readlane_b32 s3, v252, 7
	global_load_lds_dwordx4 v[2:3], off
	v_and_b32_e32 v2, 0x1800, v150
	v_lshlrev_b32_e32 v6, 7, v153
	s_add_u32 s8, s3, s10
	v_readlane_b32 s3, v252, 8
	v_or3_b32 v2, v1, v2, v6
	s_addc_u32 s9, s3, s9
	v_add_u32_e32 v2, v2, v152
	v_mov_b32_e32 v3, v143
	v_readlane_b32 s10, v252, 9
	v_lshl_add_u64 v[2:3], s[8:9], 0, v[2:3]
	s_mul_hi_i32 s3, s10, 0x160000
	s_mul_i32 s10, s10, 0x160000
	v_mov_b32_e32 v7, s3
	v_subrev_co_u32_e32 v2, vcc, s10, v2
	v_lshl_or_b32 v5, s23, 7, v156
	s_nop 0
	v_subb_co_u32_e32 v3, vcc, v3, v7, vcc
	v_lshl_add_u64 v[148:149], s[78:79], 0, v[2:3]
	v_and_b32_e32 v2, 0x3800, v154
	v_or3_b32 v2, v1, v2, v6
	v_add_u32_e32 v2, v2, v152
	v_mov_b32_e32 v3, v143
	v_lshl_add_u64 v[2:3], s[8:9], 0, v[2:3]
	s_waitcnt vmcnt(6)
	v_mov_b32_e32 v6, s3
	v_subrev_co_u32_e32 v2, vcc, s10, v2
	s_add_i32 s29, 0, 0x10000
	s_add_i32 s31, 0, 0x14000
	s_add_i32 s35, 0, 0x18000
	s_add_i32 s37, 0, 0x1c000
	v_subb_co_u32_e32 v3, vcc, v3, v6, vcc
	v_add_u32_e32 v133, s29, v5
	v_add_u32_e32 v135, s31, v5
	s_add_i32 s29, s29, s2
	s_add_i32 s31, s31, s2
	v_add_u32_e32 v139, s35, v5
	v_add_u32_e32 v158, s37, v5
	s_add_i32 s35, s35, s2
	s_add_i32 s37, s37, s2
	v_lshl_add_u64 v[150:151], s[78:79], 0, v[2:3]
	s_mov_b32 s26, -2
	s_mov_b64 s[8:9], 0x10000
	v_add_u32_e32 v137, 0, v4
	s_mov_b64 s[10:11], 0x87fc000
	s_add_i32 s27, s19, 0xc000
	s_add_i32 s28, s19, 0xe000
	s_add_i32 s30, s29, 0x2000
	s_add_i32 s34, s31, 0x2000
	s_add_i32 s36, s35, 0x2000
	s_add_i32 s38, s37, 0x2000
	v_mov_b32_e32 v2, v143
	v_mov_b32_e32 v3, v143
	v_mov_b32_e32 v4, v143
	v_mov_b32_e32 v5, v143
	v_mov_b32_e32 v6, v143
	v_mov_b32_e32 v7, v143
	v_mov_b32_e32 v8, v143
	v_mov_b32_e32 v9, v143
	v_mov_b32_e32 v14, v143
	v_mov_b32_e32 v15, v143
	v_mov_b32_e32 v16, v143
	v_mov_b32_e32 v17, v143
	v_mov_b32_e32 v22, v143
	v_mov_b32_e32 v23, v143
	v_mov_b32_e32 v24, v143
	v_mov_b32_e32 v25, v143
	v_mov_b32_e32 v30, v143
	v_mov_b32_e32 v31, v143
	v_mov_b32_e32 v32, v143
	v_mov_b32_e32 v33, v143
	v_mov_b32_e32 v38, v143
	v_mov_b32_e32 v39, v143
	v_mov_b32_e32 v40, v143
	v_mov_b32_e32 v41, v143
	v_mov_b32_e32 v46, v143
	v_mov_b32_e32 v47, v143
	v_mov_b32_e32 v48, v143
	v_mov_b32_e32 v49, v143
	v_mov_b32_e32 v54, v143
	v_mov_b32_e32 v55, v143
	v_mov_b32_e32 v56, v143
	v_mov_b32_e32 v57, v143
	v_mov_b32_e32 v10, v143
	v_mov_b32_e32 v11, v143
	v_mov_b32_e32 v12, v143
	v_mov_b32_e32 v13, v143
	v_mov_b32_e32 v18, v143
	v_mov_b32_e32 v19, v143
	v_mov_b32_e32 v20, v143
	v_mov_b32_e32 v21, v143
	v_mov_b32_e32 v26, v143
	v_mov_b32_e32 v27, v143
	v_mov_b32_e32 v28, v143
	v_mov_b32_e32 v29, v143
	v_mov_b32_e32 v34, v143
	v_mov_b32_e32 v35, v143
	v_mov_b32_e32 v36, v143
	v_mov_b32_e32 v37, v143
	v_mov_b32_e32 v42, v143
	v_mov_b32_e32 v43, v143
	v_mov_b32_e32 v44, v143
	v_mov_b32_e32 v45, v143
	v_mov_b32_e32 v50, v143
	v_mov_b32_e32 v51, v143
	v_mov_b32_e32 v52, v143
	v_mov_b32_e32 v53, v143
	v_mov_b32_e32 v58, v143
	v_mov_b32_e32 v59, v143
	v_mov_b32_e32 v60, v143
	v_mov_b32_e32 v61, v143
	v_mov_b32_e32 v62, v143
	v_mov_b32_e32 v63, v143
	v_mov_b32_e32 v64, v143
	v_mov_b32_e32 v65, v143
	v_mov_b32_e32 v66, v143
	v_mov_b32_e32 v67, v143
	v_mov_b32_e32 v68, v143
	v_mov_b32_e32 v69, v143
	v_mov_b32_e32 v70, v143
	v_mov_b32_e32 v71, v143
	v_mov_b32_e32 v72, v143
	v_mov_b32_e32 v73, v143
	v_mov_b32_e32 v78, v143
	v_mov_b32_e32 v79, v143
	v_mov_b32_e32 v80, v143
	v_mov_b32_e32 v81, v143
	v_mov_b32_e32 v86, v143
	v_mov_b32_e32 v87, v143
	v_mov_b32_e32 v88, v143
	v_mov_b32_e32 v89, v143
	v_mov_b32_e32 v94, v143
	v_mov_b32_e32 v95, v143
	v_mov_b32_e32 v96, v143
	v_mov_b32_e32 v97, v143
	v_mov_b32_e32 v102, v143
	v_mov_b32_e32 v103, v143
	v_mov_b32_e32 v104, v143
	v_mov_b32_e32 v105, v143
	v_mov_b32_e32 v110, v143
	v_mov_b32_e32 v111, v143
	v_mov_b32_e32 v112, v143
	v_mov_b32_e32 v113, v143
	v_mov_b32_e32 v118, v143
	v_mov_b32_e32 v119, v143
	v_mov_b32_e32 v120, v143
	v_mov_b32_e32 v121, v143
	v_mov_b32_e32 v74, v143
	v_mov_b32_e32 v75, v143
	v_mov_b32_e32 v76, v143
	v_mov_b32_e32 v77, v143
	v_mov_b32_e32 v82, v143
	v_mov_b32_e32 v83, v143
	v_mov_b32_e32 v84, v143
	v_mov_b32_e32 v85, v143
	v_mov_b32_e32 v90, v143
	v_mov_b32_e32 v91, v143
	v_mov_b32_e32 v92, v143
	v_mov_b32_e32 v93, v143
	v_mov_b32_e32 v98, v143
	v_mov_b32_e32 v99, v143
	v_mov_b32_e32 v100, v143
	v_mov_b32_e32 v101, v143
	v_mov_b32_e32 v106, v143
	v_mov_b32_e32 v107, v143
	v_mov_b32_e32 v108, v143
	v_mov_b32_e32 v109, v143
	v_mov_b32_e32 v114, v143
	v_mov_b32_e32 v115, v143
	v_mov_b32_e32 v116, v143
	v_mov_b32_e32 v117, v143
	v_mov_b32_e32 v122, v143
	v_mov_b32_e32 v123, v143
	v_mov_b32_e32 v124, v143
	v_mov_b32_e32 v125, v143
	v_mov_b32_e32 v126, v143
	v_mov_b32_e32 v127, v143
	v_mov_b32_e32 v128, v143
	v_mov_b32_e32 v129, v143
	s_barrier
